# baseline (speedup 1.0000x reference)
; __device__ __forceinline__ void phase_g3(PP p, const int g_wid, int wrow0, int nN, u16* P, int ldp) {
;     ...
;     EPI_TID;
;     const float* rsl = RS_LDS(par);
;     u16* Pt = P + (long)pm * 256 * ldp + pn * 256;
;     const unsigned tok0 = wc * 32 + fr;
; #pragma unroll
;     for (int bj = 0; bj < 2; ++bj)
; #pragma unroll
;       for (int n = 0; n < 2; ++n) {
;         const unsigned tok = tok0 + bj * 128 + n * 16;
;         const float rs = rsl[tok];
;         u16* pp = Pt + tok * (unsigned)ldp + wr * 64 + SWAP_FOFF(fq);
; #pragma unroll
;         for (int ai = 0; ai < 2; ++ai)
; #pragma unroll
;           for (int mp = 0; mp < 4; mp += 2) {
;             const unsigned l0 = pack2(acc[ai][bj][mp][n][0] * rs, acc[ai][bj][mp][n][1] * rs), h0 = pack2(acc[ai][bj][mp][n][2] * rs, acc[ai][bj][mp][n][3] * rs);
;             const unsigned l1 = pack2(acc[ai][bj][mp + 1][n][0] * rs, acc[ai][bj][mp + 1][n][1] * rs), h1 = pack2(acc[ai][bj][mp + 1][n][2] * rs, acc[ai][bj][mp + 1][n][3] * rs);
;             *reinterpret_cast<uint4*>(pp + ai * 128 + mp * 16) = swap_pair(l0, h0, l1, h1);
.LBB0_309:
	s_or_b64 exec, exec, s[16:17]
	s_mov_b32 s11, -1
	s_movk_i32 s13, 0x60
	v_mbcnt_lo_u32_b32 v0, s11, 0
	v_mbcnt_hi_u32_b32 v0, s11, v0
	v_readlane_b32 s11, v254, 63
	s_nop 1
	v_or_b32_e32 v0, s11, v0
	s_lshl_b32 s11, s28, 10
	v_and_b32_e32 v130, 15, v0
	v_lshrrev_b32_e32 v131, 1, v0
	s_add_i32 s11, s11, 0
	v_and_or_b32 v134, v131, s13, v130
	v_ashrrev_i32_e32 v130, 2, v0
	v_and_b32_e32 v133, 16, v0
	v_lshrrev_b32_e32 v0, 2, v0
	v_lshl_add_u32 v132, v134, 2, s11
	s_mul_hi_i32 s13, s12, s37
	s_mul_i32 s12, s12, s37
	v_and_b32_e32 v0, 12, v0
	s_lshl_b64 s[12:13], s[12:13], 1
	v_cmp_eq_u32_e32 vcc, 0, v133
	v_add_u32_e32 v133, 12, v0
	v_add_u32_e32 v135, 0x20000, v132
	s_add_u32 s11, s8, s12
	v_cndmask_b32_e32 v0, v133, v0, vcc
	ds_read2_b32 v[132:133], v135 offset1:16
	s_addc_u32 s16, s9, s13
	s_ashr_i32 s15, s14, 31
	s_lshl_b64 s[12:13], s[14:15], 1
	s_add_u32 s12, s11, s12
	v_and_b32_e32 v130, 0xffffffc0, v130
	s_addc_u32 s13, s16, s13
	v_ashrrev_i32_e32 v131, 31, v130
	v_lshl_add_u64 v[130:131], v[130:131], 1, s[12:13]
	v_and_b32_e32 v247, 63, v142
	v_lshrrev_b32_e32 v250, 6, v142
	v_lshlrev_b32_e32 v250, 14, v250
	v_and_b32_e32 v244, 15, v247
	v_lshrrev_b32_e32 v245, 4, v247
	v_and_b32_e32 v251, 1, v245
	v_lshrrev_b32_e32 v245, 1, v245
	v_lshl_or_b32 v245, v251, 1, v245
	v_and_b32_e32 v251, 7, v244
	v_xor_b32_e32 v245, v245, v251
	v_lshlrev_b32_e32 v245, 4, v245
	v_lshl_add_u32 v244, v244, 7, v250
	v_add_u32_e32 v244, v244, v245
	v_xor_b32_e32 v245, 64, v244
	v_lshrrev_b32_e32 v246, 3, v247
	v_and_b32_e32 v251, 7, v247
	v_xor_b32_e32 v247, v251, v246
	v_lshlrev_b32_e32 v247, 4, v247
	v_lshl_add_u32 v250, v246, 7, v250
	v_add_u32_e32 v250, v250, v247
	v_lshrrev_b32_e32 v247, 1, v142
	v_and_b32_e32 v247, 0x60, v247
	v_add_u32_e32 v247, v247, v246
	v_mul_u32_u24_e32 v247, s30, v247
	v_lshlrev_b32_e32 v247, 1, v247
	v_lshl_add_u32 v248, v251, 4, v247
	v_mov_b32_e32 v249, 0
	v_lshl_add_u64 v[248:249], v[130:131], 0, v[248:249]
	v_mov_b32_e32 v246, v250
	v_lshlrev_b32_e32 v0, 1, v0
	s_waitcnt lgkmcnt(0)
	v_pk_mul_f32 v[102:103], v[102:103], v[132:133] op_sel_hi:[1,0]
	v_pk_mul_f32 v[104:105], v[104:105], v[132:133] op_sel_hi:[1,0]
	v_pk_mul_f32 v[98:99], v[98:99], v[132:133] op_sel_hi:[1,0]
	v_lshl_add_u64 v[130:131], v[130:131], 0, v[0:1]
	v_mul_u32_u24_e32 v0, s30, v134
	v_cvt_pk_bf16_f32 v102, v102, v103
	v_cvt_pk_bf16_f32 v103, v104, v105
	v_cvt_pk_bf16_f32 v104, v98, v99
	v_pk_mul_f32 v[98:99], v[100:101], v[132:133] op_sel_hi:[1,0]
	v_lshlrev_b32_e32 v0, 1, v0
	v_cvt_pk_bf16_f32 v105, v98, v99
	v_lshl_add_u64 v[130:131], v[130:131], 0, v[0:1]
	v_permlane16_swap_b32_e32 v102, v104
	v_permlane16_swap_b32_e32 v103, v105
	v_pk_mul_f32 v[98:99], v[126:127], v[132:133] op_sel_hi:[1,0]
	v_pk_mul_f32 v[100:101], v[128:129], v[132:133] op_sel_hi:[1,0]
	ds_write_b128 v245, v[102:105]
	v_cvt_pk_bf16_f32 v98, v98, v99
	v_cvt_pk_bf16_f32 v99, v100, v101
	v_pk_mul_f32 v[100:101], v[122:123], v[132:133] op_sel_hi:[1,0]
	v_pk_mul_f32 v[102:103], v[124:125], v[132:133] op_sel_hi:[1,0]
	v_cvt_pk_bf16_f32 v100, v100, v101
	v_cvt_pk_bf16_f32 v101, v102, v103
	s_nop 0
	v_permlane16_swap_b32_e32 v98, v100
	v_permlane16_swap_b32_e32 v99, v101
	ds_write_b128 v244, v[98:101] offset:2048
	v_mov_b32_e32 v0, v133
	v_pk_mul_f32 v[102:103], v[108:109], v[132:133] op_sel_hi:[1,0]
	v_pk_mul_f32 v[98:99], v[110:111], v[132:133] op_sel_hi:[1,0]
	v_pk_mul_f32 v[100:101], v[112:113], v[132:133] op_sel_hi:[1,0]
	v_cvt_pk_bf16_f32 v98, v98, v99
	v_cvt_pk_bf16_f32 v99, v100, v101
	v_pk_mul_f32 v[100:101], v[106:107], v[132:133] op_sel_hi:[1,0]
	v_pk_mul_f32 v[70:71], v[70:71], v[0:1] op_sel_hi:[1,0]
	v_pk_mul_f32 v[72:73], v[72:73], v[0:1] op_sel_hi:[1,0]
	v_pk_mul_f32 v[66:67], v[66:67], v[0:1] op_sel_hi:[1,0]
	v_cvt_pk_bf16_f32 v100, v100, v101
	v_cvt_pk_bf16_f32 v101, v102, v103
	v_cvt_pk_bf16_f32 v70, v70, v71
	v_cvt_pk_bf16_f32 v71, v72, v73
	v_cvt_pk_bf16_f32 v72, v66, v67
	v_pk_mul_f32 v[66:67], v[68:69], v[0:1] op_sel_hi:[1,0]
	v_permlane16_swap_b32_e32 v98, v100
	v_permlane16_swap_b32_e32 v99, v101
	v_cvt_pk_bf16_f32 v73, v66, v67
	ds_write_b128 v245, v[98:101] offset:2048
	v_permlane16_swap_b32_e32 v70, v72
	s_nop 0
	v_lshl_add_u64 v[98:99], v[130:131], 0, s[54:55]
	v_permlane16_swap_b32_e32 v71, v73
	v_pk_mul_f32 v[66:67], v[94:95], v[0:1] op_sel_hi:[1,0]
	v_pk_mul_f32 v[68:69], v[96:97], v[0:1] op_sel_hi:[1,0]
	ds_write_b128 v245, v[70:73] offset:4096
	v_cvt_pk_bf16_f32 v66, v66, v67
	v_cvt_pk_bf16_f32 v67, v68, v69
	v_pk_mul_f32 v[68:69], v[90:91], v[0:1] op_sel_hi:[1,0]
	v_pk_mul_f32 v[70:71], v[92:93], v[0:1] op_sel_hi:[1,0]
	v_cvt_pk_bf16_f32 v68, v68, v69
	v_cvt_pk_bf16_f32 v69, v70, v71
	s_nop 0
	v_permlane16_swap_b32_e32 v66, v68
	v_permlane16_swap_b32_e32 v67, v69
	ds_write_b128 v244, v[66:69] offset:6144
	v_pk_mul_f32 v[70:71], v[76:77], v[0:1] op_sel_hi:[1,0]
	s_mov_b32 s11, s55
	v_pk_mul_f32 v[66:67], v[78:79], v[0:1] op_sel_hi:[1,0]
	v_pk_mul_f32 v[68:69], v[80:81], v[0:1] op_sel_hi:[1,0]
	v_cvt_pk_bf16_f32 v66, v66, v67
	v_cvt_pk_bf16_f32 v67, v68, v69
	v_pk_mul_f32 v[68:69], v[74:75], v[0:1] op_sel_hi:[1,0]
	v_pk_mul_f32 v[86:87], v[86:87], v[0:1] op_sel_hi:[1,0]
	v_cvt_pk_bf16_f32 v68, v68, v69
	v_cvt_pk_bf16_f32 v69, v70, v71
	s_nop 0
	v_permlane16_swap_b32_e32 v66, v68
	v_permlane16_swap_b32_e32 v67, v69
	ds_write_b128 v245, v[66:69] offset:6144
	ds_read2_b32 v[66:67], v135 offset0:128 offset1:144
	v_pk_mul_f32 v[88:89], v[88:89], v[0:1] op_sel_hi:[1,0]
	v_lshl_add_u64 v[68:69], v[98:99], 0, s[10:11]
	v_pk_mul_f32 v[82:83], v[82:83], v[0:1] op_sel_hi:[1,0]
	v_cvt_pk_bf16_f32 v86, v86, v87
	s_waitcnt lgkmcnt(0)
; __device__ __forceinline__ void phase_g3(PP p, const int g_wid, int wrow0, int nN, u16* P, int ldp) {
;     ...
; #pragma unroll
;     for (int bj = 0; bj < 2; ++bj)
; #pragma unroll
;       for (int n = 0; n < 2; ++n) {
;         const unsigned tok = tok0 + bj * 128 + n * 16;
;         const float rs = rsl[tok];
;         u16* pp = Pt + tok * (unsigned)ldp + wr * 64 + SWAP_FOFF(fq);
; #pragma unroll
;         for (int ai = 0; ai < 2; ++ai)
; #pragma unroll
;           for (int mp = 0; mp < 4; mp += 2) {
;             const unsigned l0 = pack2(acc[ai][bj][mp][n][0] * rs, acc[ai][bj][mp][n][1] * rs), h0 = pack2(acc[ai][bj][mp][n][2] * rs, acc[ai][bj][mp][n][3] * rs);
;             const unsigned l1 = pack2(acc[ai][bj][mp + 1][n][0] * rs, acc[ai][bj][mp + 1][n][1] * rs), h1 = pack2(acc[ai][bj][mp + 1][n][2] * rs, acc[ai][bj][mp + 1][n][3] * rs);
;             *reinterpret_cast<uint4*>(pp + ai * 128 + mp * 16) = swap_pair(l0, h0, l1, h1);
;           }
	v_pk_mul_f32 v[42:43], v[42:43], v[66:67] op_sel_hi:[1,0]
	v_pk_mul_f32 v[44:45], v[44:45], v[66:67] op_sel_hi:[1,0]
	v_pk_mul_f32 v[34:35], v[34:35], v[66:67] op_sel_hi:[1,0]
	v_cvt_pk_bf16_f32 v42, v42, v43
	v_cvt_pk_bf16_f32 v43, v44, v45
	v_cvt_pk_bf16_f32 v44, v34, v35
	v_pk_mul_f32 v[34:35], v[36:37], v[66:67] op_sel_hi:[1,0]
	s_nop 0
	v_permlane16_swap_b32_e32 v42, v44
	v_cvt_pk_bf16_f32 v45, v34, v35
	s_nop 1
	v_permlane16_swap_b32_e32 v43, v45
	v_pk_mul_f32 v[34:35], v[62:63], v[66:67] op_sel_hi:[1,0]
	v_pk_mul_f32 v[36:37], v[64:65], v[66:67] op_sel_hi:[1,0]
	ds_write_b128 v245, v[42:45] offset:8192
	v_cvt_pk_bf16_f32 v34, v34, v35
	v_cvt_pk_bf16_f32 v35, v36, v37
	v_pk_mul_f32 v[36:37], v[54:55], v[66:67] op_sel_hi:[1,0]
	v_pk_mul_f32 v[42:43], v[56:57], v[66:67] op_sel_hi:[1,0]
	v_cvt_pk_bf16_f32 v36, v36, v37
	v_cvt_pk_bf16_f32 v37, v42, v43
	s_nop 0
	v_permlane16_swap_b32_e32 v34, v36
	v_permlane16_swap_b32_e32 v35, v37
	v_cvt_pk_bf16_f32 v87, v88, v89
	v_cvt_pk_bf16_f32 v88, v82, v83
	v_pk_mul_f32 v[82:83], v[84:85], v[0:1] op_sel_hi:[1,0]
	ds_write_b128 v244, v[34:37] offset:10240
	v_mov_b32_e32 v0, v67
	v_pk_mul_f32 v[10:11], v[10:11], v[0:1] op_sel_hi:[1,0]
	v_pk_mul_f32 v[34:35], v[46:47], v[66:67] op_sel_hi:[1,0]
	v_pk_mul_f32 v[36:37], v[48:49], v[66:67] op_sel_hi:[1,0]
	v_cvt_pk_bf16_f32 v34, v34, v35
	v_cvt_pk_bf16_f32 v35, v36, v37
	v_pk_mul_f32 v[36:37], v[38:39], v[66:67] op_sel_hi:[1,0]
	v_pk_mul_f32 v[38:39], v[40:41], v[66:67] op_sel_hi:[1,0]
	v_pk_mul_f32 v[12:13], v[12:13], v[0:1] op_sel_hi:[1,0]
	v_pk_mul_f32 v[2:3], v[2:3], v[0:1] op_sel_hi:[1,0]
	v_cvt_pk_bf16_f32 v36, v36, v37
	v_cvt_pk_bf16_f32 v37, v38, v39
	v_cvt_pk_bf16_f32 v10, v10, v11
	v_cvt_pk_bf16_f32 v11, v12, v13
	v_cvt_pk_bf16_f32 v12, v2, v3
	v_pk_mul_f32 v[2:3], v[4:5], v[0:1] op_sel_hi:[1,0]
	v_permlane16_swap_b32_e32 v34, v36
	v_permlane16_swap_b32_e32 v35, v37
	v_cvt_pk_bf16_f32 v13, v2, v3
	ds_write_b128 v245, v[34:37] offset:10240
	v_permlane16_swap_b32_e32 v10, v12
	s_nop 0
	v_lshl_add_u64 v[34:35], v[68:69], 0, s[54:55]
	v_permlane16_swap_b32_e32 v11, v13
	v_pk_mul_f32 v[2:3], v[30:31], v[0:1] op_sel_hi:[1,0]
	v_pk_mul_f32 v[4:5], v[32:33], v[0:1] op_sel_hi:[1,0]
	ds_write_b128 v245, v[10:13] offset:12288
	v_cvt_pk_bf16_f32 v2, v2, v3
	v_cvt_pk_bf16_f32 v3, v4, v5
	v_pk_mul_f32 v[4:5], v[22:23], v[0:1] op_sel_hi:[1,0]
	v_pk_mul_f32 v[10:11], v[24:25], v[0:1] op_sel_hi:[1,0]
	v_cvt_pk_bf16_f32 v4, v4, v5
	v_cvt_pk_bf16_f32 v5, v10, v11
	s_nop 0
	v_permlane16_swap_b32_e32 v2, v4
	v_permlane16_swap_b32_e32 v3, v5
	v_pk_mul_f32 v[118:119], v[118:119], v[132:133] op_sel_hi:[1,0]
	v_pk_mul_f32 v[120:121], v[120:121], v[132:133] op_sel_hi:[1,0]
	v_pk_mul_f32 v[114:115], v[114:115], v[132:133] op_sel_hi:[1,0]
	v_pk_mul_f32 v[58:59], v[58:59], v[66:67] op_sel_hi:[1,0]
	v_pk_mul_f32 v[60:61], v[60:61], v[66:67] op_sel_hi:[1,0]
	v_pk_mul_f32 v[50:51], v[50:51], v[66:67] op_sel_hi:[1,0]
	v_pk_mul_f32 v[26:27], v[26:27], v[0:1] op_sel_hi:[1,0]
	v_pk_mul_f32 v[28:29], v[28:29], v[0:1] op_sel_hi:[1,0]
	v_pk_mul_f32 v[18:19], v[18:19], v[0:1] op_sel_hi:[1,0]
	ds_write_b128 v244, v[2:5] offset:14336
	v_cvt_pk_bf16_f32 v118, v118, v119
	v_cvt_pk_bf16_f32 v119, v120, v121
	v_pk_mul_f32 v[2:3], v[14:15], v[0:1] op_sel_hi:[1,0]
	v_pk_mul_f32 v[4:5], v[16:17], v[0:1] op_sel_hi:[1,0]
	v_cvt_pk_bf16_f32 v120, v114, v115
	v_pk_mul_f32 v[114:115], v[116:117], v[132:133] op_sel_hi:[1,0]
	v_cvt_pk_bf16_f32 v58, v58, v59
	v_cvt_pk_bf16_f32 v59, v60, v61
	v_cvt_pk_bf16_f32 v60, v50, v51
	v_pk_mul_f32 v[50:51], v[52:53], v[66:67] op_sel_hi:[1,0]
	v_cvt_pk_bf16_f32 v26, v26, v27
	v_cvt_pk_bf16_f32 v27, v28, v29
	v_cvt_pk_bf16_f32 v28, v18, v19
	v_pk_mul_f32 v[18:19], v[20:21], v[0:1] op_sel_hi:[1,0]
	v_cvt_pk_bf16_f32 v2, v2, v3
	v_cvt_pk_bf16_f32 v3, v4, v5
	v_pk_mul_f32 v[4:5], v[6:7], v[0:1] op_sel_hi:[1,0]
	v_pk_mul_f32 v[6:7], v[8:9], v[0:1] op_sel_hi:[1,0]
	v_readlane_b32 s11, v254, 4
	v_cvt_pk_bf16_f32 v121, v114, v115
	v_cvt_pk_bf16_f32 v89, v82, v83
	v_cvt_pk_bf16_f32 v61, v50, v51
	v_cvt_pk_bf16_f32 v29, v18, v19
	v_cvt_pk_bf16_f32 v4, v4, v5
	v_cvt_pk_bf16_f32 v5, v6, v7
	s_add_i32 s26, s26, s11
	s_xor_b32 s28, s28, 1
	v_permlane16_swap_b32_e32 v118, v120
	v_permlane16_swap_b32_e32 v119, v121
	v_permlane16_swap_b32_e32 v86, v88
	v_permlane16_swap_b32_e32 v87, v89
	v_permlane16_swap_b32_e32 v58, v60
	v_permlane16_swap_b32_e32 v59, v61
	v_permlane16_swap_b32_e32 v26, v28
	v_permlane16_swap_b32_e32 v27, v29
	v_permlane16_swap_b32_e32 v2, v4
	v_permlane16_swap_b32_e32 v3, v5
	ds_write_b128 v244, v[118:121]
	ds_write_b128 v244, v[86:89] offset:4096
	ds_write_b128 v244, v[58:61] offset:8192
	ds_write_b128 v244, v[26:29] offset:12288
	ds_write_b128 v245, v[2:5] offset:14336
	ds_read_b128 v[180:183], v246
	ds_read_b128 v[184:187], v246 offset:2048
	ds_read_b128 v[188:191], v246 offset:1024
	ds_read_b128 v[192:195], v246 offset:3072
	ds_read_b128 v[196:199], v246 offset:4096
	ds_read_b128 v[200:203], v246 offset:6144
	ds_read_b128 v[204:207], v246 offset:5120
	ds_read_b128 v[208:211], v246 offset:7168
	ds_read_b128 v[212:215], v246 offset:8192
	ds_read_b128 v[216:219], v246 offset:10240
	ds_read_b128 v[220:223], v246 offset:9216
	ds_read_b128 v[224:227], v246 offset:11264
	ds_read_b128 v[228:231], v246 offset:12288
	ds_read_b128 v[232:235], v246 offset:14336
	ds_read_b128 v[236:239], v246 offset:13312
	ds_read_b128 v[240:243], v246 offset:15360
	s_lshr_b32 s12, s54, 1
	s_mov_b32 s13, 0
	s_mul_i32 s14, s12, 13
	s_mov_b32 s15, 0
	s_waitcnt lgkmcnt(15)
; __device__ __forceinline__ void phase_g3(PP p, const int g_wid, int wrow0, int nN, u16* P, int ldp) {
;     ...
;             const unsigned l0 = pack2(acc[ai][bj][mp][n][0] * rs, acc[ai][bj][mp][n][1] * rs), h0 = pack2(acc[ai][bj][mp][n][2] * rs, acc[ai][bj][mp][n][3] * rs);
;             const unsigned l1 = pack2(acc[ai][bj][mp + 1][n][0] * rs, acc[ai][bj][mp + 1][n][1] * rs), h1 = pack2(acc[ai][bj][mp + 1][n][2] * rs, acc[ai][bj][mp + 1][n][3] * rs);
;             *reinterpret_cast<uint4*>(pp + ai * 128 + mp * 16) = swap_pair(l0, h0, l1, h1);
	global_store_dwordx4 v[248:249], v[180:183], off nt
	s_waitcnt lgkmcnt(14)
	global_store_dwordx4 v[248:249], v[184:187], off offset:256 nt
	v_lshl_add_u64 v[248:249], v[248:249], 0, s[12:13]
	s_waitcnt lgkmcnt(13)
	global_store_dwordx4 v[248:249], v[188:191], off nt
	s_waitcnt lgkmcnt(12)
	global_store_dwordx4 v[248:249], v[192:195], off offset:256 nt
	v_lshl_add_u64 v[248:249], v[248:249], 0, s[12:13]
	s_waitcnt lgkmcnt(11)
	global_store_dwordx4 v[248:249], v[196:199], off nt
	s_waitcnt lgkmcnt(10)
	global_store_dwordx4 v[248:249], v[200:203], off offset:256 nt
	v_lshl_add_u64 v[248:249], v[248:249], 0, s[12:13]
	s_waitcnt lgkmcnt(9)
	global_store_dwordx4 v[248:249], v[204:207], off nt
	s_waitcnt lgkmcnt(8)
	global_store_dwordx4 v[248:249], v[208:211], off offset:256 nt
	v_lshl_add_u64 v[248:249], v[248:249], 0, s[14:15]
	s_waitcnt lgkmcnt(7)
	global_store_dwordx4 v[248:249], v[212:215], off nt
	s_waitcnt lgkmcnt(6)
	global_store_dwordx4 v[248:249], v[216:219], off offset:256 nt
	v_lshl_add_u64 v[248:249], v[248:249], 0, s[12:13]
	s_waitcnt lgkmcnt(5)
	global_store_dwordx4 v[248:249], v[220:223], off nt
	s_waitcnt lgkmcnt(4)
	global_store_dwordx4 v[248:249], v[224:227], off offset:256 nt
	v_lshl_add_u64 v[248:249], v[248:249], 0, s[12:13]
	s_waitcnt lgkmcnt(3)
	global_store_dwordx4 v[248:249], v[228:231], off nt
	s_waitcnt lgkmcnt(2)
	global_store_dwordx4 v[248:249], v[232:235], off offset:256 nt
	v_lshl_add_u64 v[248:249], v[248:249], 0, s[12:13]
	s_waitcnt lgkmcnt(1)
	global_store_dwordx4 v[248:249], v[236:239], off nt
	s_waitcnt lgkmcnt(0)
	global_store_dwordx4 v[248:249], v[240:243], off offset:256 nt
	s_barrier
	s_cmp_ge_i32 s26, s27
	s_cbranch_scc1 .LBB0_322

; __device__ __forceinline__ void phase_g1(PP p, const int g_wid) {
;     ...
;     EPI_TID;
;     const float* rsl = RS_LDS(par);
;     u16* act = p->X + (long)pm * 256 * 2816 + pn * 128;
;     const unsigned tok0 = wc * 32 + fr;
; #pragma unroll
;     for (int bj = 0; bj < 2; ++bj)
; #pragma unroll
;       for (int n = 0; n < 2; ++n) {
;         const unsigned tok = tok0 + bj * 128 + n * 16;
;         const float rs = rsl[tok];
;         u16* ap = act + tok * 2816 + wr * 64 + SWAP_FOFF(fq);
;         unsigned lo[4], hi[4];
; #pragma unroll
;         for (int m = 0; m < 4; ++m) {
;           float o[4];
; #pragma unroll
;           for (int j = 0; j < 4; ++j) {
;             float g = acc[0][bj][m][n][j] * rs, u = acc[1][bj][m][n][j] * rs;
;             o[j] = g * u * __builtin_amdgcn_rcpf(1.f + __expf(-g));
;           }
;           lo[m] = pack2(o[0], o[1]); hi[m] = pack2(o[2], o[3]);
.Lg1_nopf:
	s_mov_b32 s9, -1
	v_readlane_b32 s10, v254, 0
	v_mbcnt_lo_u32_b32 v0, s9, 0
	v_mbcnt_hi_u32_b32 v0, s9, v0
	v_readlane_b32 s9, v254, 63
	v_readlane_b32 s11, v254, 1
	s_nop 0
	v_or_b32_e32 v0, s9, v0
	s_load_dwordx2 s[14:15], s[10:11], 0xd0
	v_and_b32_e32 v130, 15, v0
	s_lshl_b32 s9, s25, 10
	v_lshrrev_b32_e32 v131, 1, v0
	s_movk_i32 s10, 0x60
	s_add_i32 s9, s9, 0
	v_and_or_b32 v134, v131, s10, v130
	v_lshl_add_u32 v132, v134, 2, s9
	s_mul_hi_i32 s9, s8, 0x160000
	s_mul_i32 s8, s8, 0x160000
	s_waitcnt lgkmcnt(0)
	s_add_u32 s13, s14, s8
	v_add_u32_e32 v137, 0x20000, v132
	s_addc_u32 s14, s15, s9
	s_lshl_b32 s8, s12, 7
	ds_read2_b32 v[132:133], v137 offset1:16
	s_ashr_i32 s9, s8, 31
	v_ashrrev_i32_e32 v130, 2, v0
	v_and_b32_e32 v135, 16, v0
	v_lshrrev_b32_e32 v0, 2, v0
	s_lshl_b64 s[8:9], s[8:9], 1
	v_and_b32_e32 v0, 12, v0
	s_add_u32 s8, s13, s8
	v_and_b32_e32 v130, 0xffffffc0, v130
	v_add_u32_e32 v136, 12, v0
	v_cmp_eq_u32_e32 vcc, 0, v135
	s_addc_u32 s9, s14, s9
	v_ashrrev_i32_e32 v131, 31, v130
	v_cndmask_b32_e32 v0, v136, v0, vcc
	v_lshl_add_u64 v[130:131], v[130:131], 1, s[8:9]
	v_lshlrev_b32_e32 v0, 1, v0
	s_waitcnt lgkmcnt(0)
	v_pk_mul_f32 v[122:123], v[122:123], v[132:133] op_sel_hi:[1,0]
	v_lshl_add_u64 v[130:131], v[130:131], 0, v[0:1]
	v_mul_f32_e32 v0, 0xbfb8aa3b, v122
	v_exp_f32_e32 v0, v0
	v_mul_f32_e32 v135, 0xbfb8aa3b, v123
	v_exp_f32_e32 v135, v135
	v_mul_u32_u24_e32 v136, 0xb00, v134
	v_add_f32_e32 v0, 1.0, v0
	v_rcp_f32_e32 v134, v0
	v_add_f32_e32 v0, 1.0, v135
	v_pk_mul_f32 v[124:125], v[124:125], v[132:133] op_sel_hi:[1,0]
	v_rcp_f32_e32 v135, v0
	v_mul_f32_e32 v0, 0xbfb8aa3b, v124
	v_pk_mul_f32 v[126:127], v[126:127], v[132:133] op_sel_hi:[1,0]
	v_exp_f32_e32 v0, v0
	v_pk_mul_f32 v[122:123], v[122:123], v[126:127]
	v_mul_f32_e32 v126, 0xbfb8aa3b, v125
	v_exp_f32_e32 v127, v126
	v_add_f32_e32 v0, 1.0, v0
	v_pk_mul_f32 v[128:129], v[128:129], v[132:133] op_sel_hi:[1,0]
	v_rcp_f32_e32 v126, v0
	v_pk_mul_f32 v[124:125], v[124:125], v[128:129]
	v_add_f32_e32 v0, 1.0, v127
	v_pk_mul_f32 v[128:129], v[110:111], v[132:133] op_sel_hi:[1,0]
	v_pk_mul_f32 v[122:123], v[122:123], v[134:135]
	v_rcp_f32_e32 v127, v0
	v_mul_f32_e32 v0, 0xbfb8aa3b, v128
	v_exp_f32_e32 v0, v0
	v_cvt_pk_bf16_f32 v110, v122, v123
	v_mul_f32_e32 v122, 0xbfb8aa3b, v129
	v_exp_f32_e32 v123, v122
	v_add_f32_e32 v0, 1.0, v0
	v_pk_mul_f32 v[112:113], v[112:113], v[132:133] op_sel_hi:[1,0]
	v_pk_mul_f32 v[124:125], v[124:125], v[126:127]
	v_rcp_f32_e32 v122, v0
	v_add_f32_e32 v0, 1.0, v123
	v_mul_f32_e32 v123, 0xbfb8aa3b, v112
	v_cvt_pk_bf16_f32 v111, v124, v125
	v_exp_f32_e32 v124, v123
	v_mul_f32_e32 v123, 0xbfb8aa3b, v113
	v_exp_f32_e32 v125, v123
	v_rcp_f32_e32 v123, v0
	v_add_f32_e32 v0, 1.0, v124
	v_rcp_f32_e32 v124, v0
	v_add_f32_e32 v0, 1.0, v125
	v_rcp_f32_e32 v125, v0
	v_pk_mul_f32 v[118:119], v[118:119], v[132:133] op_sel_hi:[1,0]
	v_pk_mul_f32 v[120:121], v[120:121], v[132:133] op_sel_hi:[1,0]
	v_pk_mul_f32 v[106:107], v[106:107], v[132:133] op_sel_hi:[1,0]
	v_pk_mul_f32 v[118:119], v[128:129], v[118:119]
	v_pk_mul_f32 v[112:113], v[112:113], v[120:121]
	v_mul_f32_e32 v0, 0xbfb8aa3b, v106
	v_pk_mul_f32 v[118:119], v[118:119], v[122:123]
	v_pk_mul_f32 v[120:121], v[112:113], v[124:125]
	v_exp_f32_e32 v0, v0
	v_mul_f32_e32 v113, 0xbfb8aa3b, v107
	v_cvt_pk_bf16_f32 v112, v118, v119
	v_exp_f32_e32 v119, v113
	v_add_f32_e32 v0, 1.0, v0
	v_rcp_f32_e32 v118, v0
	v_pk_mul_f32 v[108:109], v[108:109], v[132:133] op_sel_hi:[1,0]
	v_add_f32_e32 v0, 1.0, v119
	v_rcp_f32_e32 v119, v0
	v_mul_f32_e32 v0, 0xbfb8aa3b, v108
	v_pk_mul_f32 v[114:115], v[114:115], v[132:133] op_sel_hi:[1,0]
	v_exp_f32_e32 v0, v0
	v_pk_mul_f32 v[106:107], v[106:107], v[114:115]
	v_mul_f32_e32 v114, 0xbfb8aa3b, v109
	v_exp_f32_e32 v115, v114
	v_add_f32_e32 v0, 1.0, v0
	v_rcp_f32_e32 v114, v0
	v_pk_mul_f32 v[116:117], v[116:117], v[132:133] op_sel_hi:[1,0]
	v_add_f32_e32 v0, 1.0, v115
	v_rcp_f32_e32 v115, v0
	v_pk_mul_f32 v[108:109], v[108:109], v[116:117]
	v_pk_mul_f32 v[98:99], v[98:99], v[132:133] op_sel_hi:[1,0]
	v_pk_mul_f32 v[106:107], v[106:107], v[118:119]
	v_mul_f32_e32 v0, 0xbfb8aa3b, v98
	v_pk_mul_f32 v[108:109], v[108:109], v[114:115]
	v_exp_f32_e32 v0, v0
	v_cvt_pk_bf16_f32 v106, v106, v107
	v_cvt_pk_bf16_f32 v107, v108, v109
	v_mul_f32_e32 v108, 0xbfb8aa3b, v99
	v_pk_mul_f32 v[102:103], v[102:103], v[132:133] op_sel_hi:[1,0]
	v_pk_mul_f32 v[100:101], v[100:101], v[132:133] op_sel_hi:[1,0]
	v_exp_f32_e32 v109, v108
	v_pk_mul_f32 v[98:99], v[98:99], v[102:103]
	v_mul_f32_e32 v102, 0xbfb8aa3b, v100
	v_exp_f32_e32 v102, v102
	v_mul_f32_e32 v103, 0xbfb8aa3b, v101
	v_exp_f32_e32 v103, v103
	v_add_f32_e32 v0, 1.0, v0
	v_rcp_f32_e32 v108, v0
	v_add_f32_e32 v0, 1.0, v109
	v_rcp_f32_e32 v109, v0
	v_add_f32_e32 v0, 1.0, v102
	v_rcp_f32_e32 v102, v0
	v_add_f32_e32 v0, 1.0, v103
	v_rcp_f32_e32 v103, v0
	v_pk_mul_f32 v[98:99], v[98:99], v[108:109]
	v_pk_mul_f32 v[104:105], v[104:105], v[132:133] op_sel_hi:[1,0]
	v_lshlrev_b32_e32 v0, 1, v136
	v_pk_mul_f32 v[100:101], v[100:101], v[104:105]
	v_cvt_pk_bf16_f32 v108, v98, v99
	v_lshl_add_u64 v[98:99], v[130:131], 0, v[0:1]
	v_mov_b32_e32 v0, v133
	v_pk_mul_f32 v[100:101], v[100:101], v[102:103]
	v_pk_mul_f32 v[90:91], v[90:91], v[0:1] op_sel_hi:[1,0]
	v_pk_mul_f32 v[92:93], v[92:93], v[0:1] op_sel_hi:[1,0]
	v_pk_mul_f32 v[94:95], v[94:95], v[0:1] op_sel_hi:[1,0]
	v_cvt_pk_bf16_f32 v109, v100, v101
	v_mul_f32_e32 v100, 0xbfb8aa3b, v90
	v_mul_f32_e32 v101, 0xbfb8aa3b, v91
	v_mul_f32_e32 v102, 0xbfb8aa3b, v92
	v_pk_mul_f32 v[90:91], v[90:91], v[94:95]
	v_mul_f32_e32 v95, 0xbfb8aa3b, v93
	v_exp_f32_e32 v100, v100
	v_exp_f32_e32 v101, v101
; __device__ __forceinline__ void phase_g1(PP p, const int g_wid) {
;     ...
;         const unsigned tok = tok0 + bj * 128 + n * 16;
;         const float rs = rsl[tok];
;         u16* ap = act + tok * 2816 + wr * 64 + SWAP_FOFF(fq);
;         unsigned lo[4], hi[4];
; #pragma unroll
;         for (int m = 0; m < 4; ++m) {
;           float o[4];
; #pragma unroll
;           for (int j = 0; j < 4; ++j) {
;             float g = acc[0][bj][m][n][j] * rs, u = acc[1][bj][m][n][j] * rs;
;             o[j] = g * u * __builtin_amdgcn_rcpf(1.f + __expf(-g));
;           }
;           lo[m] = pack2(o[0], o[1]); hi[m] = pack2(o[2], o[3]);
;         }
;         *reinterpret_cast<uint4*>(ap) = swap_pair(lo[0], hi[0], lo[1], hi[1]);
;         *reinterpret_cast<uint4*>(ap + 32) = swap_pair(lo[2], hi[2], lo[3], hi[3]);
	v_exp_f32_e32 v102, v102
	v_exp_f32_e32 v95, v95
	v_add_f32_e32 v100, 1.0, v100
	v_add_f32_e32 v101, 1.0, v101
	v_add_f32_e32 v94, 1.0, v102
	v_add_f32_e32 v95, 1.0, v95
	v_rcp_f32_e32 v100, v100
	v_rcp_f32_e32 v101, v101
	v_rcp_f32_e32 v94, v94
	v_rcp_f32_e32 v95, v95
	v_pk_mul_f32 v[96:97], v[96:97], v[0:1] op_sel_hi:[1,0]
	v_pk_mul_f32 v[90:91], v[90:91], v[100:101]
	v_pk_mul_f32 v[92:93], v[92:93], v[96:97]
	v_pk_mul_f32 v[96:97], v[78:79], v[0:1] op_sel_hi:[1,0]
	v_pk_mul_f32 v[92:93], v[92:93], v[94:95]
	v_mul_f32_e32 v78, 0xbfb8aa3b, v96
	v_pk_mul_f32 v[80:81], v[80:81], v[0:1] op_sel_hi:[1,0]
	v_exp_f32_e32 v100, v78
	v_cvt_pk_bf16_f32 v78, v90, v91
	v_cvt_pk_bf16_f32 v79, v92, v93
	v_mul_f32_e32 v91, 0xbfb8aa3b, v97
	v_mul_f32_e32 v92, 0xbfb8aa3b, v80
	v_mul_f32_e32 v93, 0xbfb8aa3b, v81
	v_exp_f32_e32 v91, v91
	v_exp_f32_e32 v92, v92
	v_exp_f32_e32 v93, v93
	v_add_f32_e32 v90, 1.0, v100
	v_add_f32_e32 v91, 1.0, v91
	v_add_f32_e32 v92, 1.0, v92
	v_add_f32_e32 v93, 1.0, v93
	v_rcp_f32_e32 v90, v90
	v_rcp_f32_e32 v91, v91
	v_rcp_f32_e32 v92, v92
	v_rcp_f32_e32 v93, v93
	v_pk_mul_f32 v[86:87], v[86:87], v[0:1] op_sel_hi:[1,0]
	v_pk_mul_f32 v[88:89], v[88:89], v[0:1] op_sel_hi:[1,0]
	v_pk_mul_f32 v[86:87], v[96:97], v[86:87]
	v_pk_mul_f32 v[80:81], v[80:81], v[88:89]
	v_pk_mul_f32 v[74:75], v[74:75], v[0:1] op_sel_hi:[1,0]
	v_pk_mul_f32 v[86:87], v[86:87], v[90:91]
	v_pk_mul_f32 v[88:89], v[80:81], v[92:93]
	v_mul_f32_e32 v81, 0xbfb8aa3b, v74
	v_cvt_pk_bf16_f32 v80, v86, v87
	v_exp_f32_e32 v86, v81
	v_mul_f32_e32 v81, 0xbfb8aa3b, v75
	v_pk_mul_f32 v[76:77], v[76:77], v[0:1] op_sel_hi:[1,0]
	v_pk_mul_f32 v[82:83], v[82:83], v[0:1] op_sel_hi:[1,0]
	v_exp_f32_e32 v87, v81
	v_cvt_pk_bf16_f32 v81, v88, v89
	v_mul_f32_e32 v88, 0xbfb8aa3b, v76
	v_pk_mul_f32 v[74:75], v[74:75], v[82:83]
	v_mul_f32_e32 v83, 0xbfb8aa3b, v77
	v_exp_f32_e32 v88, v88
	v_exp_f32_e32 v83, v83
	v_add_f32_e32 v86, 1.0, v86
	v_add_f32_e32 v87, 1.0, v87
	v_rcp_f32_e32 v86, v86
	v_rcp_f32_e32 v87, v87
	v_add_f32_e32 v82, 1.0, v88
	v_add_f32_e32 v83, 1.0, v83
	v_rcp_f32_e32 v82, v82
	v_rcp_f32_e32 v83, v83
	v_pk_mul_f32 v[84:85], v[84:85], v[0:1] op_sel_hi:[1,0]
	v_pk_mul_f32 v[74:75], v[74:75], v[86:87]
	v_pk_mul_f32 v[76:77], v[76:77], v[84:85]
	v_pk_mul_f32 v[84:85], v[66:67], v[0:1] op_sel_hi:[1,0]
	v_pk_mul_f32 v[76:77], v[76:77], v[82:83]
	v_mul_f32_e32 v66, 0xbfb8aa3b, v84
	v_exp_f32_e32 v86, v66
	v_cvt_pk_bf16_f32 v66, v74, v75
	v_mul_f32_e32 v75, 0xbfb8aa3b, v85
	v_pk_mul_f32 v[68:69], v[68:69], v[0:1] op_sel_hi:[1,0]
	v_cvt_pk_bf16_f32 v67, v76, v77
	v_exp_f32_e32 v75, v75
	v_mul_f32_e32 v76, 0xbfb8aa3b, v68
	v_mul_f32_e32 v77, 0xbfb8aa3b, v69
	v_exp_f32_e32 v76, v76
	v_exp_f32_e32 v77, v77
	v_add_f32_e32 v74, 1.0, v86
	v_add_f32_e32 v75, 1.0, v75
	v_rcp_f32_e32 v74, v74
	v_rcp_f32_e32 v75, v75
	v_add_f32_e32 v76, 1.0, v76
	v_add_f32_e32 v77, 1.0, v77
	v_rcp_f32_e32 v76, v76
	v_rcp_f32_e32 v77, v77
	v_pk_mul_f32 v[70:71], v[70:71], v[0:1] op_sel_hi:[1,0]
	v_pk_mul_f32 v[72:73], v[72:73], v[0:1] op_sel_hi:[1,0]
	v_pk_mul_f32 v[70:71], v[84:85], v[70:71]
	v_pk_mul_f32 v[68:69], v[68:69], v[72:73]
	v_pk_mul_f32 v[70:71], v[70:71], v[74:75]
	s_mov_b64 s[8:9], 0x16000
	v_pk_mul_f32 v[72:73], v[68:69], v[76:77]
	v_cvt_pk_bf16_f32 v68, v70, v71
	v_lshl_add_u64 v[70:71], v[98:99], 0, s[8:9]
	s_mov_b32 s8, 0x16000
	v_cvt_pk_bf16_f32 v69, v72, v73
	v_add_co_u32_e32 v72, vcc, s8, v98
	v_permlane16_swap_b32_e32 v78, v80
	v_permlane16_swap_b32_e32 v79, v81
	v_addc_co_u32_e32 v73, vcc, 0, v99, vcc
	global_store_dwordx4 v[72:73], v[78:81], off nt
	ds_read2_b32 v[72:73], v137 offset0:128 offset1:144
	v_permlane16_swap_b32_e32 v66, v68
	v_permlane16_swap_b32_e32 v67, v69
	s_waitcnt lgkmcnt(0)
	v_pk_mul_f32 v[58:59], v[58:59], v[72:73] op_sel_hi:[1,0]
	global_store_dwordx4 v[70:71], v[66:69], off offset:64 nt
	v_mul_f32_e32 v0, 0xbfb8aa3b, v58
	v_exp_f32_e32 v0, v0
	v_mul_f32_e32 v74, 0xbfb8aa3b, v59
	v_exp_f32_e32 v74, v74
	v_pk_mul_f32 v[60:61], v[60:61], v[72:73] op_sel_hi:[1,0]
	v_add_f32_e32 v0, 1.0, v0
	v_rcp_f32_e32 v66, v0
	v_add_f32_e32 v0, 1.0, v74
	v_rcp_f32_e32 v67, v0
	v_mul_f32_e32 v0, 0xbfb8aa3b, v60
	v_pk_mul_f32 v[62:63], v[62:63], v[72:73] op_sel_hi:[1,0]
	v_exp_f32_e32 v0, v0
	v_pk_mul_f32 v[58:59], v[58:59], v[62:63]
	v_mul_f32_e32 v62, 0xbfb8aa3b, v61
	v_exp_f32_e32 v63, v62
	v_add_f32_e32 v0, 1.0, v0
	v_pk_mul_f32 v[64:65], v[64:65], v[72:73] op_sel_hi:[1,0]
	v_rcp_f32_e32 v62, v0
	v_pk_mul_f32 v[60:61], v[60:61], v[64:65]
	v_add_f32_e32 v0, 1.0, v63
	v_pk_mul_f32 v[64:65], v[50:51], v[72:73] op_sel_hi:[1,0]
	v_pk_mul_f32 v[58:59], v[58:59], v[66:67]
	v_rcp_f32_e32 v63, v0
	v_mul_f32_e32 v0, 0xbfb8aa3b, v64
	v_exp_f32_e32 v0, v0
	v_cvt_pk_bf16_f32 v50, v58, v59
	v_mul_f32_e32 v58, 0xbfb8aa3b, v65
	v_exp_f32_e32 v59, v58
	v_add_f32_e32 v0, 1.0, v0
	v_pk_mul_f32 v[52:53], v[52:53], v[72:73] op_sel_hi:[1,0]
	v_pk_mul_f32 v[60:61], v[60:61], v[62:63]
	v_rcp_f32_e32 v58, v0
	v_add_f32_e32 v0, 1.0, v59
	v_mul_f32_e32 v59, 0xbfb8aa3b, v52
	v_cvt_pk_bf16_f32 v51, v60, v61
	v_exp_f32_e32 v60, v59
	v_mul_f32_e32 v59, 0xbfb8aa3b, v53
	v_exp_f32_e32 v61, v59
	v_rcp_f32_e32 v59, v0
	v_add_f32_e32 v0, 1.0, v60
	v_rcp_f32_e32 v60, v0
	v_add_f32_e32 v0, 1.0, v61
	v_rcp_f32_e32 v61, v0
	v_pk_mul_f32 v[54:55], v[54:55], v[72:73] op_sel_hi:[1,0]
	v_pk_mul_f32 v[56:57], v[56:57], v[72:73] op_sel_hi:[1,0]
	v_pk_mul_f32 v[42:43], v[42:43], v[72:73] op_sel_hi:[1,0]
	v_pk_mul_f32 v[54:55], v[64:65], v[54:55]
	v_pk_mul_f32 v[52:53], v[52:53], v[56:57]
	v_mul_f32_e32 v0, 0xbfb8aa3b, v42
	v_pk_mul_f32 v[54:55], v[54:55], v[58:59]
	v_pk_mul_f32 v[56:57], v[52:53], v[60:61]
; __device__ __forceinline__ void phase_g1(PP p, const int g_wid) {
;     ...
;     for (int bj = 0; bj < 2; ++bj)
; #pragma unroll
;       for (int n = 0; n < 2; ++n) {
;         const unsigned tok = tok0 + bj * 128 + n * 16;
;         const float rs = rsl[tok];
;         u16* ap = act + tok * 2816 + wr * 64 + SWAP_FOFF(fq);
;         unsigned lo[4], hi[4];
; #pragma unroll
;         for (int m = 0; m < 4; ++m) {
;           float o[4];
; #pragma unroll
;           for (int j = 0; j < 4; ++j) {
;             float g = acc[0][bj][m][n][j] * rs, u = acc[1][bj][m][n][j] * rs;
;             o[j] = g * u * __builtin_amdgcn_rcpf(1.f + __expf(-g));
;           }
;           lo[m] = pack2(o[0], o[1]); hi[m] = pack2(o[2], o[3]);
;         }
;         *reinterpret_cast<uint4*>(ap) = swap_pair(lo[0], hi[0], lo[1], hi[1]);
;         *reinterpret_cast<uint4*>(ap + 32) = swap_pair(lo[2], hi[2], lo[3], hi[3]);
;       }
	v_exp_f32_e32 v0, v0
	v_mul_f32_e32 v53, 0xbfb8aa3b, v43
	v_cvt_pk_bf16_f32 v52, v54, v55
	v_exp_f32_e32 v55, v53
	v_add_f32_e32 v0, 1.0, v0
	v_rcp_f32_e32 v54, v0
	v_pk_mul_f32 v[44:45], v[44:45], v[72:73] op_sel_hi:[1,0]
	v_add_f32_e32 v0, 1.0, v55
	v_rcp_f32_e32 v55, v0
	v_mul_f32_e32 v0, 0xbfb8aa3b, v44
	v_pk_mul_f32 v[46:47], v[46:47], v[72:73] op_sel_hi:[1,0]
	v_exp_f32_e32 v0, v0
	v_pk_mul_f32 v[42:43], v[42:43], v[46:47]
	v_mul_f32_e32 v46, 0xbfb8aa3b, v45
	v_exp_f32_e32 v47, v46
	v_add_f32_e32 v0, 1.0, v0
	v_pk_mul_f32 v[48:49], v[48:49], v[72:73] op_sel_hi:[1,0]
	v_rcp_f32_e32 v46, v0
	v_pk_mul_f32 v[44:45], v[44:45], v[48:49]
	v_add_f32_e32 v0, 1.0, v47
	v_pk_mul_f32 v[48:49], v[34:35], v[72:73] op_sel_hi:[1,0]
	v_pk_mul_f32 v[42:43], v[42:43], v[54:55]
	v_rcp_f32_e32 v47, v0
	v_mul_f32_e32 v0, 0xbfb8aa3b, v48
	v_exp_f32_e32 v0, v0
	v_cvt_pk_bf16_f32 v34, v42, v43
	v_mul_f32_e32 v42, 0xbfb8aa3b, v49
	v_exp_f32_e32 v43, v42
	v_add_f32_e32 v0, 1.0, v0
	v_pk_mul_f32 v[36:37], v[36:37], v[72:73] op_sel_hi:[1,0]
	v_pk_mul_f32 v[44:45], v[44:45], v[46:47]
	v_rcp_f32_e32 v42, v0
	v_add_f32_e32 v0, 1.0, v43
	v_mul_f32_e32 v43, 0xbfb8aa3b, v36
	v_cvt_pk_bf16_f32 v35, v44, v45
	v_exp_f32_e32 v44, v43
	v_mul_f32_e32 v43, 0xbfb8aa3b, v37
	v_exp_f32_e32 v45, v43
	v_rcp_f32_e32 v43, v0
	v_add_f32_e32 v0, 1.0, v44
	v_rcp_f32_e32 v44, v0
	v_add_f32_e32 v0, 1.0, v45
	v_rcp_f32_e32 v45, v0
	v_pk_mul_f32 v[38:39], v[38:39], v[72:73] op_sel_hi:[1,0]
	v_pk_mul_f32 v[40:41], v[40:41], v[72:73] op_sel_hi:[1,0]
	v_pk_mul_f32 v[38:39], v[48:49], v[38:39]
	v_pk_mul_f32 v[36:37], v[36:37], v[40:41]
	v_pk_mul_f32 v[38:39], v[38:39], v[42:43]
	s_mov_b64 s[8:9], 0xb0000
	v_pk_mul_f32 v[40:41], v[36:37], v[44:45]
	v_cvt_pk_bf16_f32 v36, v38, v39
	v_lshl_add_u64 v[38:39], v[98:99], 0, s[8:9]
	s_mov_b32 s8, 0xb0000
	v_cvt_pk_bf16_f32 v53, v56, v57
	v_cvt_pk_bf16_f32 v37, v40, v41
	v_add_co_u32_e32 v40, vcc, s8, v98
	v_mov_b32_e32 v0, v73
	v_permlane16_swap_b32_e32 v50, v52
	v_permlane16_swap_b32_e32 v51, v53
	v_addc_co_u32_e32 v41, vcc, 0, v99, vcc
	v_permlane16_swap_b32_e32 v34, v36
	v_permlane16_swap_b32_e32 v35, v37
	v_pk_mul_f32 v[26:27], v[26:27], v[0:1] op_sel_hi:[1,0]
	v_pk_mul_f32 v[28:29], v[28:29], v[0:1] op_sel_hi:[1,0]
	v_pk_mul_f32 v[30:31], v[30:31], v[0:1] op_sel_hi:[1,0]
	global_store_dwordx4 v[40:41], v[50:53], off nt
	v_mul_f32_e32 v40, 0xbfb8aa3b, v26
	v_mul_f32_e32 v41, 0xbfb8aa3b, v27
	global_store_dwordx4 v[38:39], v[34:37], off offset:64 nt
	v_pk_mul_f32 v[26:27], v[26:27], v[30:31]
	v_mul_f32_e32 v31, 0xbfb8aa3b, v29
	v_mul_f32_e32 v36, 0xbfb8aa3b, v28
	v_exp_f32_e32 v40, v40
	v_exp_f32_e32 v41, v41
	v_exp_f32_e32 v36, v36
	v_exp_f32_e32 v31, v31
	v_add_f32_e32 v34, 1.0, v40
	v_add_f32_e32 v35, 1.0, v41
	v_add_f32_e32 v30, 1.0, v36
	v_add_f32_e32 v31, 1.0, v31
	v_rcp_f32_e32 v34, v34
	v_rcp_f32_e32 v35, v35
	v_rcp_f32_e32 v30, v30
	v_rcp_f32_e32 v31, v31
	v_pk_mul_f32 v[32:33], v[32:33], v[0:1] op_sel_hi:[1,0]
	v_pk_mul_f32 v[26:27], v[26:27], v[34:35]
	v_pk_mul_f32 v[28:29], v[28:29], v[32:33]
	v_pk_mul_f32 v[32:33], v[18:19], v[0:1] op_sel_hi:[1,0]
	v_pk_mul_f32 v[28:29], v[28:29], v[30:31]
	v_mul_f32_e32 v18, 0xbfb8aa3b, v32
	v_pk_mul_f32 v[20:21], v[20:21], v[0:1] op_sel_hi:[1,0]
	v_exp_f32_e32 v34, v18
	v_cvt_pk_bf16_f32 v18, v26, v27
	v_cvt_pk_bf16_f32 v19, v28, v29
	v_mul_f32_e32 v27, 0xbfb8aa3b, v33
	v_mul_f32_e32 v28, 0xbfb8aa3b, v20
	v_mul_f32_e32 v29, 0xbfb8aa3b, v21
	v_exp_f32_e32 v27, v27
	v_exp_f32_e32 v28, v28
	v_exp_f32_e32 v29, v29
	v_add_f32_e32 v26, 1.0, v34
	v_add_f32_e32 v27, 1.0, v27
	v_add_f32_e32 v28, 1.0, v28
	v_add_f32_e32 v29, 1.0, v29
	v_rcp_f32_e32 v26, v26
	v_rcp_f32_e32 v27, v27
	v_rcp_f32_e32 v28, v28
	v_rcp_f32_e32 v29, v29
	v_pk_mul_f32 v[22:23], v[22:23], v[0:1] op_sel_hi:[1,0]
	v_pk_mul_f32 v[24:25], v[24:25], v[0:1] op_sel_hi:[1,0]
	v_pk_mul_f32 v[22:23], v[32:33], v[22:23]
	v_pk_mul_f32 v[20:21], v[20:21], v[24:25]
	v_pk_mul_f32 v[10:11], v[10:11], v[0:1] op_sel_hi:[1,0]
	v_pk_mul_f32 v[22:23], v[22:23], v[26:27]
	v_pk_mul_f32 v[24:25], v[20:21], v[28:29]
	v_mul_f32_e32 v21, 0xbfb8aa3b, v10
	v_cvt_pk_bf16_f32 v20, v22, v23
	v_exp_f32_e32 v22, v21
	v_mul_f32_e32 v21, 0xbfb8aa3b, v11
	v_pk_mul_f32 v[12:13], v[12:13], v[0:1] op_sel_hi:[1,0]
	v_pk_mul_f32 v[14:15], v[14:15], v[0:1] op_sel_hi:[1,0]
	v_exp_f32_e32 v23, v21
	v_cvt_pk_bf16_f32 v21, v24, v25
	v_mul_f32_e32 v24, 0xbfb8aa3b, v12
	v_pk_mul_f32 v[10:11], v[10:11], v[14:15]
	v_mul_f32_e32 v15, 0xbfb8aa3b, v13
	v_exp_f32_e32 v24, v24
	v_exp_f32_e32 v15, v15
	v_add_f32_e32 v22, 1.0, v22
	v_add_f32_e32 v23, 1.0, v23
	v_rcp_f32_e32 v22, v22
	v_rcp_f32_e32 v23, v23
	v_add_f32_e32 v14, 1.0, v24
	v_add_f32_e32 v15, 1.0, v15
	v_rcp_f32_e32 v14, v14
	v_rcp_f32_e32 v15, v15
	v_pk_mul_f32 v[16:17], v[16:17], v[0:1] op_sel_hi:[1,0]
	v_pk_mul_f32 v[10:11], v[10:11], v[22:23]
	v_pk_mul_f32 v[12:13], v[12:13], v[16:17]
	v_pk_mul_f32 v[16:17], v[2:3], v[0:1] op_sel_hi:[1,0]
	v_pk_mul_f32 v[12:13], v[12:13], v[14:15]
	v_mul_f32_e32 v2, 0xbfb8aa3b, v16
	v_exp_f32_e32 v22, v2
	v_cvt_pk_bf16_f32 v2, v10, v11
	v_mul_f32_e32 v11, 0xbfb8aa3b, v17
	v_pk_mul_f32 v[4:5], v[4:5], v[0:1] op_sel_hi:[1,0]
	v_cvt_pk_bf16_f32 v3, v12, v13
	v_exp_f32_e32 v11, v11
	v_mul_f32_e32 v12, 0xbfb8aa3b, v4
	v_mul_f32_e32 v13, 0xbfb8aa3b, v5
	v_exp_f32_e32 v12, v12
	v_exp_f32_e32 v13, v13
	v_add_f32_e32 v10, 1.0, v22
	v_add_f32_e32 v11, 1.0, v11
	v_rcp_f32_e32 v10, v10
	v_rcp_f32_e32 v11, v11
	v_add_f32_e32 v12, 1.0, v12
	v_add_f32_e32 v13, 1.0, v13
	v_rcp_f32_e32 v12, v12
	v_rcp_f32_e32 v13, v13
	v_pk_mul_f32 v[6:7], v[6:7], v[0:1] op_sel_hi:[1,0]
	v_pk_mul_f32 v[8:9], v[8:9], v[0:1] op_sel_hi:[1,0]
	v_pk_mul_f32 v[6:7], v[16:17], v[6:7]
	v_pk_mul_f32 v[4:5], v[4:5], v[8:9]
	v_pk_mul_f32 v[6:7], v[6:7], v[10:11]
	s_mov_b64 s[8:9], 0xc6000
	v_pk_mul_f32 v[8:9], v[4:5], v[12:13]
	v_cvt_pk_bf16_f32 v4, v6, v7
	v_lshl_add_u64 v[6:7], v[98:99], 0, s[8:9]
	v_readlane_b32 s8, v254, 4
	v_cvt_pk_bf16_f32 v113, v120, v121
	v_cvt_pk_bf16_f32 v5, v8, v9
	v_add_co_u32_e32 v8, vcc, 0xc6000, v98
	s_xor_b32 s25, s25, 1
	v_permlane16_swap_b32_e32 v110, v112
	v_permlane16_swap_b32_e32 v111, v113
	v_permlane16_swap_b32_e32 v106, v108
	v_permlane16_swap_b32_e32 v107, v109
	v_permlane16_swap_b32_e32 v18, v20
	v_permlane16_swap_b32_e32 v19, v21
	v_addc_co_u32_e32 v9, vcc, 0, v99, vcc
	v_permlane16_swap_b32_e32 v2, v4
	v_permlane16_swap_b32_e32 v3, v5
	s_cmpk_lt_i32 s24, 0x1096
	global_store_dwordx4 v[98:99], v[110:113], off nt
	global_store_dwordx4 v[98:99], v[106:109], off offset:64 nt
	global_store_dwordx4 v[8:9], v[18:21], off nt
	global_store_dwordx4 v[6:7], v[2:5], off offset:64 nt
	s_cbranch_scc0 .LBB0_468
